# plus unit-loop headers: division by the panel-group size (always 8 for M=16384) replaced by shift and mask
# baseline (speedup 1.0000x reference)
;     __host__ __device__ bool next(int i, Unit& u) const {
;         const long L = (long)i * G + c; if (L >= nwg) return false;
;         int wgid = (int)L; { const int q = nwg / NXCD, r = nwg % NXCD, xcd = wgid % NXCD, off = wgid / NXCD; wgid = (xcd < r ? xcd * (q + 1) : r * (q + 1) + (xcd - r) * q) + off; }
;         const int nig = WGM * nN, gid = wgid / nig, fm = gid * WGM, gsz = (nM - fm) < WGM ? (nM - fm) : WGM;
;         u.pm = fm + ((wgid % nig) % gsz); u.pn = (wgid % nig) / gsz; return true;
.LBB0_140:
	s_add_i32 s72, s72, 1
	s_mul_i32 s4, s72, s71
	s_mul_hi_u32 s5, s72, s3
	s_add_i32 s5, s5, s4
	s_mul_i32 s4, s72, s3
	s_add_u32 s30, s4, s2
	s_addc_u32 s31, s5, s73
	v_cmp_gt_i64_e32 vcc, s[30:31], v[142:143]
	v_cmp_lt_i64_e64 s[4:5], s[30:31], v[140:141]
	s_cbranch_vccnz .LBB0_142
	s_ashr_i32 s7, s30, 31
	s_lshr_b32 s7, s7, 29
	s_add_i32 s7, s30, s7
	s_ashr_i32 s26, s7, 3
	s_and_b32 s7, s7, -8
	s_sub_i32 s7, s30, s7
	s_cmp_lt_i32 s7, 0
	s_cselect_b32 s27, s76, 0xb0
	s_mul_i32 s7, s7, s27
	s_add_i32 s7, s7, s26
	s_mul_hi_i32 s26, s7, 0x2e8ba2e9
	s_lshr_b32 s27, s26, 31
	s_ashr_i32 s26, s26, 5
	s_add_i32 s26, s26, s27
	s_lshl_b32 s27, s26, 3
	s_sub_i32 s28, 64, s27
	s_min_i32 s28, s28, 8
	s_mulk_i32 s26, 0xb0
	s_sub_i32 s7, s7, s26
	s_lshr_b32 s26, s7, 3
	s_and_b32 s7, s7, 7
	s_add_i32 s28, s27, s7

;     __host__ __device__ bool next(int i, Unit& u) const {
;     ...
;         int wgid = (int)L; { const int q = nwg / NXCD, r = nwg % NXCD, xcd = wgid % NXCD, off = wgid / NXCD; wgid = (xcd < r ? xcd * (q + 1) : r * (q + 1) + (xcd - r) * q) + off; }
;         const int nig = WGM * nN, gid = wgid / nig, fm = gid * WGM, gsz = (nM - fm) < WGM ? (nM - fm) : WGM;
;         u.pm = fm + ((wgid % nig) % gsz); u.pn = (wgid % nig) / gsz; return true;
.LBB0_360:
	s_ashr_i32 s6, s16, 3
	s_add_i32 s6, s20, s6
	s_ashr_i32 s7, s6, 31
	s_lshr_b32 s7, s7, 27
	s_add_i32 s7, s6, s7
	s_ashr_i32 s16, s7, 5
	s_lshl_b32 s16, s16, 3
	s_sub_i32 s17, 64, s16
	s_min_i32 s17, s17, 8
	s_andn2_b32 s7, s7, 31
	s_sub_i32 s6, s6, s7
	s_lshr_b32 s61, s6, 3
	s_and_b32 s6, s6, 7
	s_add_i32 s62, s16, s6

;     __host__ __device__ bool next(int i, Unit& u) const {
;     ...
;         int wgid = (int)L; { const int q = nwg / NXCD, r = nwg % NXCD, xcd = wgid % NXCD, off = wgid / NXCD; wgid = (xcd < r ? xcd * (q + 1) : r * (q + 1) + (xcd - r) * q) + off; }
;         const int nig = WGM * nN, gid = wgid / nig, fm = gid * WGM, gsz = (nM - fm) < WGM ? (nM - fm) : WGM;
;         u.pm = fm + ((wgid % nig) % gsz); u.pn = (wgid % nig) / gsz; return true;
.LBB0_460:
	s_ashr_i32 s7, s7, 3
	s_add_i32 s7, s67, s7
	s_ashr_i32 s52, s7, 31
	s_lshr_b32 s52, s52, 26
	s_add_i32 s52, s7, s52
	s_ashr_i32 s53, s52, 6
	s_lshl_b32 s53, s53, 3
	s_sub_i32 s64, 64, s53
	s_min_i32 s65, s64, 8
	s_andn2_b32 s52, s52, 63
	s_sub_i32 s7, s7, s52
	s_lshr_b32 s64, s7, 3
	s_and_b32 s7, s7, 7
	s_add_i32 s66, s53, s7

;     __host__ __device__ bool next(int i, Unit& u) const {
;         const long L = (long)i * G + c; if (L >= nwg) return false;
;         int wgid = (int)L; { const int q = nwg / NXCD, r = nwg % NXCD, xcd = wgid % NXCD, off = wgid / NXCD; wgid = (xcd < r ? xcd * (q + 1) : r * (q + 1) + (xcd - r) * q) + off; }
;         const int nig = WGM * nN, gid = wgid / nig, fm = gid * WGM, gsz = (nM - fm) < WGM ? (nM - fm) : WGM;
;         u.pm = fm + ((wgid % nig) % gsz); u.pn = (wgid % nig) / gsz; return true;
.LBB0_593:
	s_add_i32 s97, s97, 1
	s_mul_i32 s4, s97, s59
	s_mul_hi_u32 s5, s97, s25
	s_add_i32 s5, s5, s4
	s_mul_i32 s4, s97, s25
	s_add_u32 s68, s4, s2
	s_addc_u32 s69, s5, s85
	v_cmp_gt_i64_e32 vcc, s[68:69], v[146:147]
	v_cmp_lt_i64_e64 s[4:5], s[68:69], v[144:145]
	s_cbranch_vccnz .LBB0_595
	s_ashr_i32 s7, s68, 31
	s_lshr_b32 s7, s7, 29
	s_add_i32 s7, s68, s7
	s_ashr_i32 s9, s7, 3
	s_and_b32 s7, s7, -8
	s_sub_i32 s7, s68, s7
	s_cmp_lt_i32 s7, 0
	s_cselect_b32 s18, 49, 48
	s_mul_i32 s7, s7, s18
	s_add_i32 s7, s7, s9
	s_mul_hi_i32 s9, s7, 0x2aaaaaab
	s_lshr_b32 s18, s9, 31
	s_ashr_i32 s9, s9, 3
	s_add_i32 s9, s9, s18
	s_lshl_b32 s18, s9, 3
	s_sub_i32 s52, 64, s18
	s_min_i32 s52, s52, 8
	s_mul_i32 s9, s9, 48
	s_sub_i32 s7, s7, s9
	s_lshr_b32 s64, s7, 3
	s_and_b32 s7, s7, 7
	s_add_i32 s66, s18, s7

;     __host__ __device__ bool next(int i, Unit& u) const {
;     ...
;         int wgid = (int)L; { const int q = nwg / NXCD, r = nwg % NXCD, xcd = wgid % NXCD, off = wgid / NXCD; wgid = (xcd < r ? xcd * (q + 1) : r * (q + 1) + (xcd - r) * q) + off; }
;         const int nig = WGM * nN, gid = wgid / nig, fm = gid * WGM, gsz = (nM - fm) < WGM ? (nM - fm) : WGM;
;         u.pm = fm + ((wgid % nig) % gsz); u.pn = (wgid % nig) / gsz; return true;
.LBB0_1007:
	s_ashr_i32 s16, s18, 3
	s_add_i32 s16, s20, s16
	s_ashr_i32 s17, s16, 31
	s_lshr_b32 s17, s17, 27
	s_add_i32 s17, s16, s17
	s_ashr_i32 s18, s17, 5
	s_lshl_b32 s18, s18, 3
	s_sub_i32 s19, 64, s18
	s_min_i32 s19, s19, 8
	s_andn2_b32 s17, s17, 31
	s_sub_i32 s17, s16, s17
	s_lshr_b32 s16, s17, 3
	s_and_b32 s17, s17, 7
	s_add_i32 s18, s18, s17

;     __host__ __device__ bool next(int i, Unit& u) const {
;         const long L = (long)i * G + c; if (L >= nwg) return false;
;         int wgid = (int)L; { const int q = nwg / NXCD, r = nwg % NXCD, xcd = wgid % NXCD, off = wgid / NXCD; wgid = (xcd < r ? xcd * (q + 1) : r * (q + 1) + (xcd - r) * q) + off; }
;         const int nig = WGM * nN, gid = wgid / nig, fm = gid * WGM, gsz = (nM - fm) < WGM ? (nM - fm) : WGM;
;         u.pm = fm + ((wgid % nig) % gsz); u.pn = (wgid % nig) / gsz; return true;
.LBB0_1268:
	s_add_i32 s74, s74, 1
	s_mul_i32 s4, s74, s71
	s_mul_hi_u32 s5, s74, s3
	s_add_i32 s5, s5, s4
	s_mul_i32 s4, s74, s3
	s_add_u32 s28, s4, s2
	s_addc_u32 s29, s5, s65
	v_cmp_gt_i64_e32 vcc, s[28:29], v[142:143]
	v_cmp_lt_i64_e64 s[4:5], s[28:29], v[140:141]
	s_cbranch_vccnz .LBB0_1270
	s_ashr_i32 s24, s28, 31
	s_lshr_b32 s24, s24, 29
	s_add_i32 s24, s28, s24
	s_ashr_i32 s25, s24, 3
	s_and_b32 s24, s24, -8
	s_sub_i32 s24, s28, s24
	s_cmp_lt_i32 s24, 0
	s_cselect_b32 s26, s66, 0xb0
	s_mul_i32 s24, s24, s26
	s_add_i32 s24, s24, s25
	s_mul_hi_i32 s25, s24, 0x2e8ba2e9
	s_lshr_b32 s26, s25, 31
	s_ashr_i32 s25, s25, 5
	s_add_i32 s25, s25, s26
	s_lshl_b32 s26, s25, 3
	s_sub_i32 s27, 64, s26
	s_min_i32 s27, s27, 8
	s_mulk_i32 s25, 0xb0
	s_sub_i32 s25, s24, s25
	s_lshr_b32 s24, s25, 3
	s_and_b32 s25, s25, 7
	s_add_i32 s26, s26, s25

;     __host__ __device__ bool next(int i, Unit& u) const {
;     ...
;         int wgid = (int)L; { const int q = nwg / NXCD, r = nwg % NXCD, xcd = wgid % NXCD, off = wgid / NXCD; wgid = (xcd < r ? xcd * (q + 1) : r * (q + 1) + (xcd - r) * q) + off; }
;         const int nig = WGM * nN, gid = wgid / nig, fm = gid * WGM, gsz = (nM - fm) < WGM ? (nM - fm) : WGM;
;         u.pm = fm + ((wgid % nig) % gsz); u.pn = (wgid % nig) / gsz; return true;
.LBB0_1424:
	s_ashr_i32 s6, s16, 3
	s_add_i32 s6, s20, s6
	s_ashr_i32 s7, s6, 31
	s_lshr_b32 s7, s7, 27
	s_add_i32 s7, s6, s7
	s_ashr_i32 s16, s7, 5
	s_lshl_b32 s16, s16, 3
	s_sub_i32 s17, 64, s16
	s_min_i32 s17, s17, 8
	s_andn2_b32 s7, s7, 31
	s_sub_i32 s6, s6, s7
	s_lshr_b32 s43, s6, 3
	s_and_b32 s6, s6, 7
	s_add_i32 s44, s16, s6
